# nt hint on P1's read-once f32 x-row loads (input stream no longer displaces XS / converted weights from the caches)
# speedup vs baseline: 1.0059x; 1.0059x over previous
.LBB0_122:
	s_and_b64 s[50:51], s[50:51], exec
	s_cselect_b32 s51, s53, 0
	s_cselect_b32 s50, s52, s57
	s_cselect_b32 s54, s9, s11
	s_cselect_b32 s55, s8, s10
	s_lshl_b64 s[50:51], s[50:51], 12
	s_add_u32 s50, s55, s50
	s_addc_u32 s51, s54, s51
	s_mul_i32 s54, s56, 0x6000
	s_mul_hi_i32 s55, s56, 0x6000
	s_add_u32 s54, s14, s54
	s_addc_u32 s55, s15, s55
	v_lshl_add_u64 v[20:21], s[54:55], 0, v[88:89]
	s_waitcnt lgkmcnt(0)
	v_lshl_add_u64 v[18:19], s[50:51], 0, v[88:89]
	v_lshl_add_u64 v[22:23], v[20:21], 0, s[48:49]
	v_add_co_u32_e32 v20, vcc, s64, v20
	s_add_i32 s70, s52, s61
	s_nop 0
	v_addc_co_u32_e32 v21, vcc, 0, v21, vcc
	global_load_dwordx4 v[74:77], v[18:19], off nt
	global_load_dwordx4 v[70:73], v[18:19], off offset:1024 nt
	global_load_dwordx4 v[58:61], v[22:23], off offset:1024
	global_load_dwordx4 v[46:49], v[22:23], off offset:2048
	global_load_dwordx4 v[54:57], v[18:19], off offset:2048 nt
	global_load_dwordx4 v[38:41], v[18:19], off offset:3072 nt
	global_load_dwordx4 v[78:81], v[20:21], off
	global_load_dwordx4 v[42:45], v[22:23], off offset:3072
	s_cmpk_gt_i32 s70, 0x41ff
	s_cselect_b32 s50, s52, s70
	s_cmpk_lt_i32 s50, 0x4000
	s_cselect_b64 s[54:55], -1, 0
	s_add_i32 s72, s50, 0xffffc000
	s_mov_b64 s[56:57], -1
	s_and_b64 vcc, exec, s[54:55]
	s_cbranch_vccnz .LBB0_124
	s_lshr_b32 s51, s72, 4
	s_add_i32 s71, s51, 2
	s_mov_b64 s[56:57], 0

.LBB0_126:
	s_and_b64 s[54:55], exec, s[54:55]
	s_cselect_b32 s55, s51, 0
	s_cselect_b32 s54, s50, s72
	s_cselect_b32 s56, s9, s11
	s_cselect_b32 s57, s8, s10
	s_lshl_b64 s[54:55], s[54:55], 12
	s_add_u32 s54, s57, s54
	s_addc_u32 s55, s56, s55
	s_mul_i32 s56, s71, 0x6000
	s_mul_hi_i32 s57, s71, 0x6000
	s_add_u32 s56, s14, s56
	s_addc_u32 s57, s15, s57
	v_lshl_add_u64 v[20:21], s[56:57], 0, v[88:89]
	v_add_co_u32_e32 v24, vcc, s64, v20
	v_lshl_add_u64 v[18:19], s[54:55], 0, v[88:89]
	v_lshl_add_u64 v[22:23], v[20:21], 0, s[48:49]
	v_addc_co_u32_e32 v25, vcc, 0, v21, vcc
	global_load_dwordx4 v[62:65], v[18:19], off nt
	global_load_dwordx4 v[50:53], v[18:19], off offset:1024 nt
	global_load_dwordx4 v[34:37], v[22:23], off offset:1024
	global_load_dwordx4 v[26:29], v[22:23], off offset:2048
	global_load_dwordx4 v[30:33], v[18:19], off offset:2048 nt
	s_nop 0
	global_load_dwordx4 v[18:21], v[18:19], off offset:3072 nt
	s_nop 0
	global_load_dwordx4 v[66:69], v[24:25], off
	s_nop 0
	global_load_dwordx4 v[22:25], v[22:23], off offset:3072
	s_waitcnt vmcnt(15)
	v_mul_f32_e32 v98, v75, v75
	v_fmac_f32_e32 v98, v74, v74
	v_mul_f32_e32 v99, v77, v77
	v_pk_mul_f32 v[74:75], v[2:3], v[74:75]
	s_waitcnt vmcnt(9)
	v_pk_add_f32 v[78:79], v[78:79], 1.0 op_sel_hi:[1,0]
	s_lshl_b64 s[54:55], s[52:53], 11
	v_fmac_f32_e32 v99, v76, v76
	v_pk_mul_f32 v[76:77], v[4:5], v[76:77]
	v_pk_add_f32 v[80:81], v[80:81], 1.0 op_sel_hi:[1,0]
	v_pk_mul_f32 v[74:75], v[74:75], v[78:79]
	v_lshl_add_u64 v[96:97], v[84:85], 0, s[54:55]
	v_pk_mul_f32 v[76:77], v[76:77], v[80:81]
	v_cvt_pk_bf16_f32 v74, v74, v75
	v_add_f32_e32 v98, v98, v99
	v_cvt_pk_bf16_f32 v75, v76, v77
	global_store_dwordx2 v[96:97], v[74:75], off
	v_mul_f32_e32 v74, v71, v71
	v_mul_f32_e32 v75, v73, v73
	v_fmac_f32_e32 v74, v70, v70
	v_fmac_f32_e32 v75, v72, v72
	v_add_f32_e32 v74, v74, v75
	v_mul_f32_e32 v75, v55, v55
	v_mul_f32_e32 v76, v57, v57
	v_fmac_f32_e32 v75, v54, v54
	v_fmac_f32_e32 v76, v56, v56
	v_add_f32_e32 v74, v98, v74
	v_add_f32_e32 v75, v75, v76
	v_add_f32_e32 v74, v74, v75
	v_mul_f32_e32 v75, v39, v39
	v_mul_f32_e32 v76, v41, v41
	v_fmac_f32_e32 v75, v38, v38
	v_fmac_f32_e32 v76, v40, v40
	v_add_f32_e32 v75, v75, v76
	v_add_f32_e32 v74, v74, v75
	ds_bpermute_b32 v75, v82, v74
	v_pk_mul_f32 v[70:71], v[6:7], v[70:71]
	v_pk_add_f32 v[58:59], v[58:59], 1.0 op_sel_hi:[1,0]
	v_pk_mul_f32 v[72:73], v[8:9], v[72:73]
	v_pk_mul_f32 v[58:59], v[70:71], v[58:59]
	s_waitcnt lgkmcnt(0)
	v_add_f32_e32 v70, v74, v75
	ds_bpermute_b32 v71, v91, v70
	v_pk_add_f32 v[60:61], v[60:61], 1.0 op_sel_hi:[1,0]
	v_cvt_pk_bf16_f32 v58, v58, v59
	v_pk_mul_f32 v[54:55], v[10:11], v[54:55]
	v_pk_mul_f32 v[60:61], v[72:73], v[60:61]
	v_pk_add_f32 v[46:47], v[46:47], 1.0 op_sel_hi:[1,0]
	v_cvt_pk_bf16_f32 v59, v60, v61
	global_store_dwordx2 v[96:97], v[58:59], off offset:512
	s_waitcnt lgkmcnt(0)
	v_add_f32_e32 v58, v70, v71
	ds_bpermute_b32 v59, v92, v58
	v_pk_mul_f32 v[46:47], v[54:55], v[46:47]
	v_pk_mul_f32 v[56:57], v[12:13], v[56:57]
	v_pk_add_f32 v[48:49], v[48:49], 1.0 op_sel_hi:[1,0]
	v_cvt_pk_bf16_f32 v46, v46, v47
	s_waitcnt lgkmcnt(0)
	v_add_f32_e32 v54, v58, v59
	ds_bpermute_b32 v55, v93, v54
	v_pk_mul_f32 v[48:49], v[56:57], v[48:49]
	v_pk_mul_f32 v[40:41], v[16:17], v[40:41]
	v_cvt_pk_bf16_f32 v47, v48, v49
	global_store_dwordx2 v[96:97], v[46:47], off offset:1024
	s_waitcnt lgkmcnt(0)
	v_add_f32_e32 v48, v54, v55
	ds_bpermute_b32 v49, v94, v48
	v_pk_mul_f32 v[46:47], v[14:15], v[38:39]
	s_waitcnt vmcnt(11)
	v_pk_add_f32 v[38:39], v[44:45], 1.0 op_sel_hi:[1,0]
	v_pk_add_f32 v[42:43], v[42:43], 1.0 op_sel_hi:[1,0]
	v_pk_mul_f32 v[40:41], v[40:41], v[38:39]
	s_waitcnt lgkmcnt(0)
	v_add_f32_e32 v38, v48, v49
	ds_bpermute_b32 v39, v95, v38
	v_pk_mul_f32 v[42:43], v[46:47], v[42:43]
	s_nop 0
	v_cvt_pk_bf16_f32 v42, v42, v43
	v_cvt_pk_bf16_f32 v43, v40, v41
	global_store_dwordx2 v[96:97], v[42:43], off offset:1536
	s_and_saveexec_b64 s[54:55], s[6:7]
	s_cbranch_execz .LBB0_128
	s_waitcnt lgkmcnt(0)
	v_add_f32_e32 v38, v38, v39
	s_lshl_b64 s[52:53], s[52:53], 6
	v_cndmask_b32_e64 v40, 0, v38, s[4:5]
	v_lshl_add_u64 v[38:39], v[86:87], 0, s[52:53]
	global_store_dword v[38:39], v40, off
